# hyena filter images: the eight h3-row loads of a t-tile requested together at the top of the tile (was four dependent pairs)
# baseline (speedup 1.0000x reference)
.LBB0_260:
	v_add_u32_e32 v46, s53, v57
	v_ashrrev_i32_e32 v47, 31, v46
	v_lshlrev_b64 v[2:3], 8, v[46:47]
	v_lshl_add_u64 v[14:15], v[36:37], 0, v[2:3]
	global_load_dwordx4 v[2:5], v[14:15], off
	global_load_dwordx4 v[6:9], v[14:15], off offset:16
	global_load_dwordx4 v[100:103], v[14:15], off offset:64
	global_load_dwordx4 v[104:107], v[14:15], off offset:80
	global_load_dwordx4 v[108:111], v[14:15], off offset:128
	global_load_dwordx4 v[112:115], v[14:15], off offset:144
	global_load_dwordx4 v[68:71], v[14:15], off offset:192
	global_load_dwordx4 v[72:75], v[14:15], off offset:208
	v_add_u32_e32 v44, s53, v56
	v_add_u32_e32 v45, 1, v44
	v_add_u32_e32 v47, 2, v44
	v_add_u32_e32 v76, 3, v44
	v_cvt_f32_i32_e32 v45, v45
	v_cvt_f32_i32_e32 v47, v47
	v_cvt_f32_i32_e32 v76, v76
	v_cvt_f32_i32_e32 v34, v44
	v_mul_f32_e64 v45, v59, -v45
	v_mul_f32_e64 v47, v59, -v47
	v_mul_f32_e32 v45, 0x3fb8aa3b, v45
	v_mul_f32_e32 v47, 0x3fb8aa3b, v47
	v_mul_f32_e64 v34, v59, -v34
	v_mul_f32_e32 v34, 0x3fb8aa3b, v34
	v_exp_f32_e32 v34, v34
	v_cmp_eq_u32_e64 s[0:1], s53, v58
	s_waitcnt vmcnt(7)
	v_cvt_pk_bf16_f32 v2, v2, v3
	v_cvt_pk_bf16_f32 v3, v4, v5
	s_waitcnt vmcnt(6)
	v_cvt_pk_bf16_f32 v4, v6, v7
	v_cvt_pk_bf16_f32 v5, v8, v9
	v_add_f32_e32 v34, 0x3d4ccccd, v34
	s_waitcnt vmcnt(5)
	v_cvt_pk_bf16_f32 v60, v100, v101
	v_cvt_pk_bf16_f32 v61, v102, v103
	s_waitcnt vmcnt(4)
	v_cvt_pk_bf16_f32 v62, v104, v105
	v_cvt_pk_bf16_f32 v63, v106, v107
	s_waitcnt vmcnt(3)
	v_cvt_pk_bf16_f32 v64, v108, v109
	v_cvt_pk_bf16_f32 v65, v110, v111
	s_waitcnt vmcnt(2)
	v_cvt_pk_bf16_f32 v66, v112, v113
	v_cvt_pk_bf16_f32 v67, v114, v115
	v_mfma_f32_32x32x16_bf16 v[2:17], v[2:5], v[18:21], 0
	v_mfma_f32_32x32x16_bf16 v[2:17], v[60:63], v[22:25], v[2:17]
	v_mul_f32_e64 v60, v59, -v76
	v_mul_f32_e32 v62, 0x3fb8aa3b, v60
	v_exp_f32_e32 v60, v45
	v_exp_f32_e32 v61, v47
	v_exp_f32_e32 v45, v62
	s_nop 0
	v_add_f32_e32 v45, 0x3d4ccccd, v45
	v_mfma_f32_32x32x16_bf16 v[2:17], v[64:67], v[26:29], v[2:17]
	v_add_f32_e64 v64, v60, s10
	v_add_f32_e64 v65, v61, s10
	s_waitcnt vmcnt(1)
	v_cvt_pk_bf16_f32 v60, v68, v69
	v_cvt_pk_bf16_f32 v61, v70, v71
	s_waitcnt vmcnt(0)
	v_cvt_pk_bf16_f32 v62, v72, v73
	v_cvt_pk_bf16_f32 v63, v74, v75
	s_nop 0
	v_mfma_f32_32x32x16_bf16 v[2:17], v[60:63], v[30:33], v[2:17]
	s_nop 11
	v_mul_f32_e32 v47, v34, v2
	v_fma_f32 v34, v34, v2, v54
	v_mov_b32_e32 v2, v3
	v_mov_b32_e32 v3, v4
	v_cndmask_b32_e64 v34, v47, v34, s[0:1]
	v_pk_mul_f32 v[2:3], v[64:65], v[2:3]
	v_mul_f32_e32 v4, v45, v5
	s_and_saveexec_b64 s[0:1], vcc
	s_xor_b64 s[34:35], exec, s[0:1]
	s_cbranch_execz .LBB0_266
	v_cmp_ne_u32_e64 s[0:1], s53, v55
	s_and_saveexec_b64 s[54:55], s[0:1]
	s_xor_b64 s[0:1], exec, s[54:55]
	s_cbranch_execz .LBB0_263
	v_ashrrev_i32_e32 v45, 31, v44
	v_cvt_pk_bf16_f32 v2, v34, v2
	v_cvt_pk_bf16_f32 v3, v3, v4
	v_lshl_add_u64 v[4:5], v[44:45], 1, v[40:41]
	global_store_dwordx2 v[4:5], v[2:3], off

.LBB0_280:
	s_or_b64 exec, exec, s[0:1]
	v_add_u32_e32 v2, 32, v46
	v_ashrrev_i32_e32 v3, 31, v2
	v_lshlrev_b64 v[2:3], 8, v[2:3]
	v_lshl_add_u64 v[14:15], v[36:37], 0, v[2:3]
	global_load_dwordx4 v[2:5], v[14:15], off
	global_load_dwordx4 v[6:9], v[14:15], off offset:16
	global_load_dwordx4 v[100:103], v[14:15], off offset:64
	global_load_dwordx4 v[104:107], v[14:15], off offset:80
	global_load_dwordx4 v[108:111], v[14:15], off offset:128
	global_load_dwordx4 v[112:115], v[14:15], off offset:144
	global_load_dwordx4 v[68:71], v[14:15], off offset:192
	global_load_dwordx4 v[72:75], v[14:15], off offset:208
	v_add_u32_e32 v46, 32, v44
	v_add_u32_e32 v34, 33, v44
	v_add_u32_e32 v76, 35, v44
	v_cvt_f32_i32_e32 v77, v46
	v_cvt_f32_i32_e32 v34, v34
	v_cvt_f32_i32_e32 v76, v76
	v_add_u32_e32 v47, 34, v44
	v_cvt_f32_i32_e32 v47, v47
	v_mul_f32_e64 v77, v59, -v77
	v_mul_f32_e64 v34, v59, -v34
	v_mul_f32_e32 v34, 0x3fb8aa3b, v34
	v_mul_f32_e64 v47, v59, -v47
	v_mul_f32_e32 v47, 0x3fb8aa3b, v47
	s_waitcnt vmcnt(7)
	v_cvt_pk_bf16_f32 v2, v2, v3
	v_cvt_pk_bf16_f32 v3, v4, v5
	s_waitcnt vmcnt(6)
	v_cvt_pk_bf16_f32 v4, v6, v7
	v_cvt_pk_bf16_f32 v5, v8, v9
	s_waitcnt vmcnt(5)
	v_cvt_pk_bf16_f32 v60, v100, v101
	v_cvt_pk_bf16_f32 v61, v102, v103
	s_waitcnt vmcnt(4)
	v_cvt_pk_bf16_f32 v62, v104, v105
	v_cvt_pk_bf16_f32 v63, v106, v107
	s_waitcnt vmcnt(3)
	v_cvt_pk_bf16_f32 v64, v108, v109
	v_cvt_pk_bf16_f32 v65, v110, v111
	s_waitcnt vmcnt(2)
	v_cvt_pk_bf16_f32 v66, v112, v113
	v_cvt_pk_bf16_f32 v67, v114, v115
	v_mfma_f32_32x32x16_bf16 v[2:17], v[2:5], v[18:21], 0
	v_mfma_f32_32x32x16_bf16 v[2:17], v[60:63], v[22:25], v[2:17]
	v_mul_f32_e64 v60, v59, -v76
	v_mul_f32_e32 v61, 0x3fb8aa3b, v77
	v_mul_f32_e32 v60, 0x3fb8aa3b, v60
	v_exp_f32_e32 v76, v61
	v_mfma_f32_32x32x16_bf16 v[2:17], v[64:67], v[26:29], v[2:17]
	v_exp_f32_e32 v64, v34
	v_exp_f32_e32 v34, v60
	v_exp_f32_e32 v65, v47
	v_add_f32_e32 v47, 0x3d4ccccd, v76
	s_waitcnt vmcnt(1)
	v_cvt_pk_bf16_f32 v60, v68, v69
	v_cvt_pk_bf16_f32 v61, v70, v71
	s_waitcnt vmcnt(0)
	v_cvt_pk_bf16_f32 v62, v72, v73
	v_cvt_pk_bf16_f32 v63, v74, v75
	s_nop 0
	v_mfma_f32_32x32x16_bf16 v[2:17], v[60:63], v[30:33], v[2:17]
	v_add_f32_e64 v60, v64, s10
	v_add_f32_e64 v61, v65, s10
	v_add_f32_e32 v62, 0x3d4ccccd, v34
	s_nop 8
	v_mul_f32_e32 v34, v47, v2
	v_mov_b32_e32 v2, v3
	v_mov_b32_e32 v3, v4
	v_pk_mul_f32 v[2:3], v[60:61], v[2:3]
	v_mul_f32_e32 v4, v62, v5
	s_and_saveexec_b64 s[0:1], vcc
	s_xor_b64 s[0:1], exec, s[0:1]
	s_cbranch_execz .LBB0_282
	v_ashrrev_i32_e32 v47, 31, v46
	v_cvt_pk_bf16_f32 v2, v34, v2
	v_cvt_pk_bf16_f32 v3, v3, v4
	v_lshl_add_u64 v[4:5], v[46:47], 1, v[40:41]
	global_store_dwordx2 v[4:5], v[2:3], off

.LBB0_304:
	v_add_u32_e32 v46, s24, v59
	v_ashrrev_i32_e32 v47, 31, v46
	v_lshlrev_b64 v[2:3], 8, v[46:47]
	v_lshl_add_u64 v[14:15], v[36:37], 0, v[2:3]
	global_load_dwordx4 v[2:5], v[14:15], off
	global_load_dwordx4 v[6:9], v[14:15], off offset:16
	global_load_dwordx4 v[100:103], v[14:15], off offset:64
	global_load_dwordx4 v[104:107], v[14:15], off offset:80
	global_load_dwordx4 v[108:111], v[14:15], off offset:128
	global_load_dwordx4 v[112:115], v[14:15], off offset:144
	global_load_dwordx4 v[70:73], v[14:15], off offset:192
	global_load_dwordx4 v[74:77], v[14:15], off offset:208
	v_add_u32_e32 v44, s24, v58
	v_add_u32_e32 v45, 1, v44
	v_add_u32_e32 v47, 2, v44
	v_add_u32_e32 v78, 3, v44
	v_cvt_f32_i32_e32 v45, v45
	v_cvt_f32_i32_e32 v47, v47
	v_cvt_f32_i32_e32 v78, v78
	v_cvt_f32_i32_e32 v34, v44
	v_mul_f32_e64 v45, v61, -v45
	v_mul_f32_e64 v47, v61, -v47
	v_mul_f32_e32 v45, 0x3fb8aa3b, v45
	v_mul_f32_e32 v47, 0x3fb8aa3b, v47
	v_mul_f32_e64 v34, v61, -v34
	v_mul_f32_e32 v34, 0x3fb8aa3b, v34
	v_exp_f32_e32 v34, v34
	v_cmp_eq_u32_e64 s[0:1], s24, v60
	s_waitcnt vmcnt(7)
	v_cvt_pk_bf16_f32 v2, v2, v3
	v_cvt_pk_bf16_f32 v3, v4, v5
	s_waitcnt vmcnt(6)
	v_cvt_pk_bf16_f32 v4, v6, v7
	v_cvt_pk_bf16_f32 v5, v8, v9
	v_add_f32_e32 v34, 0x3d4ccccd, v34
	s_waitcnt vmcnt(5)
	v_cvt_pk_bf16_f32 v62, v100, v101
	v_cvt_pk_bf16_f32 v63, v102, v103
	s_waitcnt vmcnt(4)
	v_cvt_pk_bf16_f32 v64, v104, v105
	v_cvt_pk_bf16_f32 v65, v106, v107
	s_waitcnt vmcnt(3)
	v_cvt_pk_bf16_f32 v66, v108, v109
	v_cvt_pk_bf16_f32 v67, v110, v111
	s_waitcnt vmcnt(2)
	v_cvt_pk_bf16_f32 v68, v112, v113
	v_cvt_pk_bf16_f32 v69, v114, v115
	v_mfma_f32_32x32x16_bf16 v[2:17], v[2:5], v[18:21], 0
	v_mfma_f32_32x32x16_bf16 v[2:17], v[62:65], v[22:25], v[2:17]
	v_mul_f32_e64 v62, v61, -v78
	v_mul_f32_e32 v64, 0x3fb8aa3b, v62
	v_exp_f32_e32 v62, v45
	v_exp_f32_e32 v63, v47
	v_exp_f32_e32 v45, v64
	s_nop 0
	v_add_f32_e32 v45, 0x3d4ccccd, v45
	v_mfma_f32_32x32x16_bf16 v[2:17], v[66:69], v[26:29], v[2:17]
	v_add_f32_e64 v66, v62, s10
	v_add_f32_e64 v67, v63, s10
	s_waitcnt vmcnt(1)
	v_cvt_pk_bf16_f32 v62, v70, v71
	v_cvt_pk_bf16_f32 v63, v72, v73
	s_waitcnt vmcnt(0)
	v_cvt_pk_bf16_f32 v64, v74, v75
	v_cvt_pk_bf16_f32 v65, v76, v77
	s_nop 0
	v_mfma_f32_32x32x16_bf16 v[2:17], v[62:65], v[30:33], v[2:17]
	s_nop 11
	v_mul_f32_e32 v47, v34, v2
	v_fma_f32 v34, v34, v2, v56
	v_mov_b32_e32 v2, v3
	v_mov_b32_e32 v3, v4
	v_cndmask_b32_e64 v34, v47, v34, s[0:1]
	v_pk_mul_f32 v[2:3], v[66:67], v[2:3]
	v_mul_f32_e32 v4, v45, v5
	s_and_saveexec_b64 s[0:1], vcc
	s_xor_b64 s[22:23], exec, s[0:1]
	s_cbranch_execz .LBB0_310
	v_cmp_ne_u32_e64 s[0:1], s24, v57
	s_and_saveexec_b64 s[26:27], s[0:1]
	s_xor_b64 s[0:1], exec, s[26:27]
	s_cbranch_execz .LBB0_307
	v_ashrrev_i32_e32 v45, 31, v44
	v_cvt_pk_bf16_f32 v2, v34, v2
	v_cvt_pk_bf16_f32 v3, v3, v4
	v_lshl_add_u64 v[4:5], v[44:45], 1, v[40:41]
	global_store_dwordx2 v[4:5], v[2:3], off offset:512

.LBB0_324:
	s_or_b64 exec, exec, s[0:1]
	v_add_u32_e32 v2, 32, v46
	v_ashrrev_i32_e32 v3, 31, v2
	v_lshlrev_b64 v[2:3], 8, v[2:3]
	v_lshl_add_u64 v[14:15], v[36:37], 0, v[2:3]
	global_load_dwordx4 v[2:5], v[14:15], off
	global_load_dwordx4 v[6:9], v[14:15], off offset:16
	global_load_dwordx4 v[100:103], v[14:15], off offset:64
	global_load_dwordx4 v[104:107], v[14:15], off offset:80
	global_load_dwordx4 v[108:111], v[14:15], off offset:128
	global_load_dwordx4 v[112:115], v[14:15], off offset:144
	global_load_dwordx4 v[70:73], v[14:15], off offset:192
	global_load_dwordx4 v[74:77], v[14:15], off offset:208
	v_add_u32_e32 v45, 33, v44
	v_add_u32_e32 v78, 35, v44
	v_cvt_f32_i32_e32 v45, v45
	v_cvt_f32_i32_e32 v78, v78
	v_add_u32_e32 v34, 32, v44
	v_add_u32_e32 v46, 34, v44
	v_cvt_f32_i32_e32 v34, v34
	v_cvt_f32_i32_e32 v46, v46
	v_mul_f32_e64 v45, v61, -v45
	v_mul_f32_e32 v45, 0x3fb8aa3b, v45
	v_mul_f32_e64 v34, v61, -v34
	v_mul_f32_e64 v46, v61, -v46
	v_mul_f32_e32 v34, 0x3fb8aa3b, v34
	v_mul_f32_e32 v46, 0x3fb8aa3b, v46
	v_exp_f32_e32 v34, v34
	s_waitcnt vmcnt(7)
	v_cvt_pk_bf16_f32 v2, v2, v3
	v_cvt_pk_bf16_f32 v3, v4, v5
	s_waitcnt vmcnt(6)
	v_cvt_pk_bf16_f32 v4, v6, v7
	v_cvt_pk_bf16_f32 v5, v8, v9
	v_add_f32_e32 v34, 0x3d4ccccd, v34
	s_waitcnt vmcnt(5)
	v_cvt_pk_bf16_f32 v62, v100, v101
	v_cvt_pk_bf16_f32 v63, v102, v103
	s_waitcnt vmcnt(4)
	v_cvt_pk_bf16_f32 v64, v104, v105
	v_cvt_pk_bf16_f32 v65, v106, v107
	s_waitcnt vmcnt(3)
	v_cvt_pk_bf16_f32 v66, v108, v109
	v_cvt_pk_bf16_f32 v67, v110, v111
	s_waitcnt vmcnt(2)
	v_cvt_pk_bf16_f32 v68, v112, v113
	v_cvt_pk_bf16_f32 v69, v114, v115
	v_mfma_f32_32x32x16_bf16 v[2:17], v[2:5], v[18:21], 0
	v_mfma_f32_32x32x16_bf16 v[2:17], v[62:65], v[22:25], v[2:17]
	v_mul_f32_e64 v62, v61, -v78
	v_mul_f32_e32 v62, 0x3fb8aa3b, v62
	v_mfma_f32_32x32x16_bf16 v[2:17], v[66:69], v[26:29], v[2:17]
	v_exp_f32_e32 v66, v45
	v_exp_f32_e32 v45, v62
	v_exp_f32_e32 v67, v46
	s_waitcnt vmcnt(1)
	v_cvt_pk_bf16_f32 v62, v70, v71
	v_cvt_pk_bf16_f32 v63, v72, v73
	s_waitcnt vmcnt(0)
	v_cvt_pk_bf16_f32 v64, v74, v75
	v_cvt_pk_bf16_f32 v65, v76, v77
	v_add_f32_e32 v45, 0x3d4ccccd, v45
	v_mfma_f32_32x32x16_bf16 v[2:17], v[62:65], v[30:33], v[2:17]
	v_add_f32_e64 v62, v66, s10
	v_add_f32_e64 v63, v67, s10
	s_nop 9
	v_mul_f32_e32 v34, v34, v2
	v_mov_b32_e32 v2, v3
	v_mov_b32_e32 v3, v4
	v_pk_mul_f32 v[2:3], v[62:63], v[2:3]
	v_mul_f32_e32 v4, v45, v5
	s_and_saveexec_b64 s[0:1], vcc
	s_xor_b64 s[0:1], exec, s[0:1]
	s_cbranch_execz .LBB0_326
	v_cvt_pk_bf16_f32 v2, v34, v2
	v_cvt_pk_bf16_f32 v3, v3, v4
	global_store_dwordx2 v[42:43], v[2:3], off
